# attn loop: K/V staging (ds_write + next global loads) interleaved into the QK MFMA gaps instead of a separate MFMA-free block
# baseline (speedup 1.0000x reference)
; #define SBAR() __builtin_amdgcn_sched_barrier(0)
; __device__ __forceinline__ void finishSM(f32x16& p0, f32x16& p1, float alpha, float& l_reg, bf16x8& pa0, bf16x8& pa1, bf16x8& pa2, bf16x8& pa3) {
; #pragma unroll
;   for (int r = 0; r < 16; ++r) p1[r] = __builtin_amdgcn_exp2f(p1[r]);
;   float ps = 0;
; #pragma unroll
;   for (int r = 0; r < 16; ++r) ps += p0[r];
; #pragma unroll
;   for (int r = 0; r < 16; ++r) ps += p1[r];
;   { auto rr = __builtin_amdgcn_permlane32_swap(__float_as_uint(ps), __float_as_uint(ps), false, false);
;     ps = __uint_as_float(rr[0]) + __uint_as_float(rr[1]); }
;   l_reg = l_reg * alpha + ps;
;     ...
;   PK4(p0, 0, pa0); PK4(p0, 8, pa1); PK4(p1, 0, pa2); PK4(p1, 8, pa3);
;     ...
; }
; __device__ __forceinline__ void qkt(f32x16& p0, f32x16& p1, const char* Ks, const bf16x8* qr, const char* qrl, int r32, int hi) {
;   p0 = f32x16{}; p1 = f32x16{};
; #pragma unroll
;   for (int d0 = 0; d0 < 8; ++d0) { int cb = (d0 * 16 + hi * 8) * 2;
;     bf16x8 b0 = *reinterpret_cast<const bf16x8*>(Ks + KSWZ(r32, cb));
;     bf16x8 b1 = *reinterpret_cast<const bf16x8*>(Ks + KSWZ(32 + r32, cb));
;     p0 = __builtin_amdgcn_mfma_f32_32x32x16_bf16(b0, qr[d0], p0, 0, 0, 0);
;     p1 = __builtin_amdgcn_mfma_f32_32x32x16_bf16(b1, qr[d0], p1, 0, 0, 0); }
; #pragma unroll
;   for (int d0 = 8; d0 < 12; ++d0) { int cb = (d0 * 16 + hi * 8) * 2;
;     bf16x8 b0 = *reinterpret_cast<const bf16x8*>(Ks + KSWZ(r32, cb));
;     bf16x8 b1 = *reinterpret_cast<const bf16x8*>(Ks + KSWZ(32 + r32, cb));
;     bf16x8 qf = *reinterpret_cast<const bf16x8*>(qrl + (((2 * (d0 - 8) + hi) ^ ((r32 >> 1) & 7)) << 4));
;     p0 = __builtin_amdgcn_mfma_f32_32x32x16_bf16(b0, qf, p0, 0, 0, 0);
;     p1 = __builtin_amdgcn_mfma_f32_32x32x16_bf16(b1, qf, p1, 0, 0, 0); }
; }
; __device__ __forceinline__ void attn_unit(const bf16_t* __restrict__ Qb, const bf16_t* __restrict__ Kn, const bf16_t* __restrict__ Vh, const bf16_t* __restrict__ Kr,
;                                           bf16_t* GO, int seq, char* lds, const int tid) {
;     ...
;     SWRITE(bn, 0); SLOAD(0, (j + 2) * KVBLK); SBAR();
.LBB0_1151:
	s_sub_i32 s30, s76, 1
	s_cmp_eq_u32 s76, 0
	s_cselect_b32 s30, 2, s30
	s_add_i32 s18, s76, 1
	s_cmp_lg_u32 s76, 2
	s_cselect_b32 s18, s18, 0
	ds_read_b128 v[64:67], v199 offset:36864
	ds_read_b128 v[68:71], v199 offset:49152
	ds_read_b128 v[232:235], v205 offset:36864
	ds_read_b128 v[236:239], v205 offset:49152
	ds_read_b128 v[240:243], v206 offset:36864
	ds_read_b128 v[248:251], v206 offset:49152
	v_exp_f32_e32 v162, v162
	v_add_f32_e32 v211, v225, v228
	v_exp_f32_e32 v163, v163
	v_add_f32_e32 v211, v226, v211
	v_exp_f32_e32 v160, v160
	s_waitcnt lgkmcnt(4)
	v_mfma_f32_32x32x16_bf16 v[80:95], v[64:67], v[124:127], 0
	v_add_f32_e32 v211, v229, v211
	v_exp_f32_e32 v161, v161
	v_add_f32_e32 v211, v227, v211
	v_mfma_f32_32x32x16_bf16 v[64:79], v[68:71], v[124:127], 0
	v_exp_f32_e32 v158, v158
	v_add_f32_e32 v211, v230, v211
	v_exp_f32_e32 v159, v159
	s_waitcnt lgkmcnt(2)
	v_mfma_f32_32x32x16_bf16 v[80:95], v[232:235], v[120:123], v[80:95]
	ds_read_b128 v[232:235], v208 offset:36864
	v_add_f32_e32 v211, v223, v211
	v_exp_f32_e32 v156, v156
	v_add_f32_e32 v211, v224, v211
	v_mfma_f32_32x32x16_bf16 v[64:79], v[236:239], v[120:123], v[64:79]
	ds_read_b128 v[236:239], v208 offset:49152
	v_exp_f32_e32 v157, v157
	v_add_f32_e32 v211, v219, v211
	v_exp_f32_e32 v154, v154
	s_waitcnt lgkmcnt(2)
	v_mfma_f32_32x32x16_bf16 v[80:95], v[240:243], v[116:119], v[80:95]
	ds_read_b128 v[240:243], v207 offset:36864
	v_add_f32_e32 v211, v221, v211
	v_exp_f32_e32 v155, v155
	v_add_f32_e32 v211, v220, v211
	v_mfma_f32_32x32x16_bf16 v[64:79], v[248:251], v[116:119], v[64:79]
	ds_read_b128 v[248:251], v207 offset:49152
	v_exp_f32_e32 v152, v152
	v_add_f32_e32 v211, v222, v211
	v_exp_f32_e32 v153, v153
	s_waitcnt lgkmcnt(2)
	v_mfma_f32_32x32x16_bf16 v[80:95], v[232:235], v[112:115], v[80:95]
	ds_read_b128 v[232:235], v204 offset:36864
	v_add_f32_e32 v211, v215, v211
	v_exp_f32_e32 v150, v150
	v_add_f32_e32 v211, v217, v211
	v_mfma_f32_32x32x16_bf16 v[64:79], v[236:239], v[112:115], v[64:79]
	ds_read_b128 v[236:239], v204 offset:49152
	v_exp_f32_e32 v151, v151
	v_add_f32_e32 v211, v216, v211
	v_exp_f32_e32 v148, v148
	s_waitcnt lgkmcnt(2)
	v_mfma_f32_32x32x16_bf16 v[80:95], v[240:243], v[108:111], v[80:95]
	ds_read_b128 v[240:243], v203 offset:36864
	v_add_f32_e32 v211, v218, v211
	v_exp_f32_e32 v149, v149
	v_add_f32_e32 v212, v162, v163
	v_add_f32_e32 v212, v160, v212
	v_mfma_f32_32x32x16_bf16 v[64:79], v[248:251], v[108:111], v[64:79]
	ds_read_b128 v[248:251], v203 offset:49152
	v_add_f32_e32 v212, v161, v212
	v_add_f32_e32 v212, v158, v212
	v_add_f32_e32 v212, v159, v212
	v_add_f32_e32 v212, v156, v212
	v_add_f32_e32 v212, v157, v212
	s_waitcnt lgkmcnt(2)
	v_mfma_f32_32x32x16_bf16 v[80:95], v[232:235], v[104:107], v[80:95]
	ds_read_b128 v[232:235], v200 offset:36864
	v_add_f32_e32 v212, v154, v212
	v_add_f32_e32 v212, v155, v212
	v_add_f32_e32 v212, v152, v212
	v_add_f32_e32 v212, v153, v212
	v_add_f32_e32 v212, v150, v212
	v_mfma_f32_32x32x16_bf16 v[64:79], v[236:239], v[104:107], v[64:79]
	ds_read_b128 v[236:239], v200 offset:49152
	v_add_f32_e32 v212, v151, v212
	v_add_f32_e32 v212, v148, v212
	v_add_f32_e32 v212, v149, v212
	v_add_f32_e32 v211, v211, v212
	v_mov_b32_e32 v212, v211
	s_lshl_b32 s19, s18, 14
	v_add_u32_e32 v231, s19, v183
	s_waitcnt lgkmcnt(2)
	v_mfma_f32_32x32x16_bf16 v[80:95], v[240:243], v[100:103], v[80:95]
	ds_read_b128 v[240:243], v191 offset:36864
	s_waitcnt vmcnt(0)
	ds_write_b128 v231, v[140:143]
	v_add_u32_e32 v140, s19, v184
	ds_write_b128 v140, v[144:147]
	ds_write_b128 v185, v[136:139] offset:12288
	ds_write_b128 v185, v[132:135] offset:24576
	s_mov_b32 s18, 0xfffa0000
	v_mfma_f32_32x32x16_bf16 v[64:79], v[248:251], v[100:103], v[64:79]
	ds_read_b128 v[248:251], v202 offset:49152
	ds_write_b128 v186, v[128:131] offset:12288
	v_add_co_u32_e32 v128, vcc, s18, v168
	s_mov_b32 s18, 0xfffc0000
	s_nop 0
	v_addc_co_u32_e32 v129, vcc, -1, v169, vcc
	v_add_co_u32_e32 v130, vcc, s18, v168
	s_movk_i32 s18, 0xe000
	s_nop 0
	v_addc_co_u32_e32 v131, vcc, -1, v169, vcc
	s_waitcnt lgkmcnt(7)
; #define SBAR() __builtin_amdgcn_sched_barrier(0)
; __device__ __forceinline__ void finishSM(f32x16& p0, f32x16& p1, float alpha, float& l_reg, bf16x8& pa0, bf16x8& pa1, bf16x8& pa2, bf16x8& pa3) {
; #pragma unroll
;   for (int r = 0; r < 16; ++r) p1[r] = __builtin_amdgcn_exp2f(p1[r]);
;   float ps = 0;
; #pragma unroll
;   for (int r = 0; r < 16; ++r) ps += p0[r];
; #pragma unroll
;   for (int r = 0; r < 16; ++r) ps += p1[r];
;   { auto rr = __builtin_amdgcn_permlane32_swap(__float_as_uint(ps), __float_as_uint(ps), false, false);
;     ps = __uint_as_float(rr[0]) + __uint_as_float(rr[1]); }
;   l_reg = l_reg * alpha + ps;
;     ...
;   PK4(p0, 0, pa0); PK4(p0, 8, pa1); PK4(p1, 0, pa2); PK4(p1, 8, pa3);
;     ...
; }
; __device__ __forceinline__ void attn_unit(const bf16_t* __restrict__ Qb, const bf16_t* __restrict__ Kn, const bf16_t* __restrict__ Vh, const bf16_t* __restrict__ Kr,
;                                           bf16_t* GO, int seq, char* lds, const int tid) {
;     ...
;     SWRITE(bn, 0); SLOAD(0, (j + 2) * KVBLK); SBAR();
;     pv_d0(o, vb0 + bp * SHM_V, pa0, pa1, pa2, pa3); partialSM(pB0, pB1, m_reg, mnB, alB);
	v_mfma_f32_32x32x16_bf16 v[80:95], v[232:235], v[96:99], v[80:95]
	ds_read_b128 v[232:235], v182
	global_load_dwordx4 v[140:143], v[128:129], off
	global_load_dwordx4 v[136:139], v[128:129], off offset:-256
	global_load_dwordx4 v[144:147], v[130:131], off
	global_load_dwordx4 v[132:135], v[130:131], off offset:-256
	v_add_co_u32_e32 v128, vcc, s18, v166
	s_nop 1
	v_mfma_f32_32x32x16_bf16 v[64:79], v[236:239], v[96:99], v[64:79]
	ds_read_b128 v[236:239], v198 offset:36864
	v_addc_co_u32_e32 v129, vcc, -1, v167, vcc
	global_load_dwordx4 v[128:131], v[128:129], off
	v_cvt_pk_bf16_f32 v158, v158, v159
	v_cvt_pk_bf16_f32 v159, v156, v157
	v_permlane32_swap_b32_e32 v211, v212
	s_waitcnt lgkmcnt(1)
	v_mfma_f32_32x32x16_bf16 v[80:95], v[240:243], v[232:235], v[80:95]
	ds_read_b128 v[240:243], v201 offset:49152
	v_cvt_pk_bf16_f32 v156, v162, v163
	v_cvt_pk_bf16_f32 v157, v160, v161
	v_cvt_pk_bf16_f32 v160, v154, v155
	v_cvt_pk_bf16_f32 v161, v152, v153
	v_cvt_pk_bf16_f32 v162, v150, v151
	v_mfma_f32_32x32x16_bf16 v[64:79], v[248:251], v[232:235], v[64:79]
	ds_read_b128 v[248:251], v181
	ds_read_b128 v[232:235], v187 offset:36864
	v_cvt_pk_bf16_f32 v163, v148, v149
	v_add_f32_e32 v211, v211, v212
	v_cvt_pk_bf16_f32 v148, v225, v228
	v_cvt_pk_bf16_f32 v149, v226, v229
	v_cvt_pk_bf16_f32 v150, v227, v230
	s_waitcnt lgkmcnt(1)
	v_mfma_f32_32x32x16_bf16 v[80:95], v[236:239], v[248:251], v[80:95]
	ds_read_b128 v[236:239], v189 offset:49152
	v_cvt_pk_bf16_f32 v151, v223, v224
	v_cvt_pk_bf16_f32 v152, v219, v221
	v_cvt_pk_bf16_f32 v153, v220, v222
	v_cvt_pk_bf16_f32 v154, v215, v217
	v_cvt_pk_bf16_f32 v155, v216, v218
	v_mfma_f32_32x32x16_bf16 v[64:79], v[240:243], v[248:251], v[64:79]
	ds_read_b128 v[240:243], v179
	ds_read_b128 v[248:251], v188 offset:36864
	v_fma_f32 v176, v209, v176, v211
	s_waitcnt lgkmcnt(1)
	v_mfma_f32_32x32x16_bf16 v[80:95], v[232:235], v[240:243], v[80:95]
	ds_read_b128 v[232:235], v190 offset:49152
	v_mfma_f32_32x32x16_bf16 v[64:79], v[236:239], v[240:243], v[64:79]
	ds_read_b128 v[236:239], v177
	s_waitcnt lgkmcnt(0)
	v_mfma_f32_32x32x16_bf16 v[80:95], v[248:251], v[236:239], v[80:95]
	v_mfma_f32_32x32x16_bf16 v[64:79], v[232:235], v[236:239], v[64:79]
	s_lshl_b32 s31, s30, 14
	v_add_u32_e32 v180, s31, v178
	ds_read_b64_tr_b16 v[240:241], v180 offset:0
	ds_read_b64_tr_b16 v[242:243], v180 offset:2048
	ds_read_b64_tr_b16 v[248:249], v180 offset:512
	ds_read_b64_tr_b16 v[250:251], v180 offset:2560
	ds_read_b64_tr_b16 v[232:233], v180 offset:1024
	ds_read_b64_tr_b16 v[234:235], v180 offset:3072
	ds_read_b64_tr_b16 v[236:237], v180 offset:1536
	ds_read_b64_tr_b16 v[238:239], v180 offset:3584
	s_nop 3
	v_max3_f32 v194, v80, v81, v82
	v_max3_f32 v195, v64, v65, v66
	v_max3_f32 v194, v194, v83, v84
	v_max3_f32 v195, v195, v67, v68
	v_max3_f32 v194, v194, v85, v86
	v_max3_f32 v195, v195, v69, v70
	s_waitcnt lgkmcnt(4)
	v_mfma_f32_32x32x16_bf16 v[32:47], v[148:151], v[240:243], v[32:47]
	ds_read_b64_tr_b16 v[240:241], v180 offset:4096
	ds_read_b64_tr_b16 v[242:243], v180 offset:6144
	v_max3_f32 v194, v194, v87, v88
	v_max3_f32 v195, v195, v71, v72
	v_max3_f32 v194, v194, v89, v90
	v_max3_f32 v195, v195, v73, v74
	v_max3_f32 v194, v194, v91, v92
	v_max3_f32 v195, v195, v75, v76
	v_mfma_f32_32x32x16_bf16 v[48:63], v[148:151], v[248:251], v[48:63]
	ds_read_b64_tr_b16 v[248:249], v180 offset:4608
	ds_read_b64_tr_b16 v[250:251], v180 offset:6656
	v_max3_f32 v194, v194, v93, v94
	v_max3_f32 v195, v195, v77, v78
	v_max3_f32 v194, v194, v95, v195
	v_max_f32_e32 v194, v194, v79
	v_mov_b32_e32 v195, v194
	s_nop 1
	s_waitcnt lgkmcnt(4)
	v_mfma_f32_32x32x16_bf16 v[16:31], v[148:151], v[232:235], v[16:31]
	ds_read_b64_tr_b16 v[232:233], v180 offset:5120
	ds_read_b64_tr_b16 v[234:235], v180 offset:7168
	v_permlane32_swap_b32_e32 v194, v195
	v_max_f32_e32 v194, v194, v195
	v_sub_f32_e32 v195, v194, v210
	v_cmp_ge_f32_e32 vcc, s15, v195
	v_mfma_f32_32x32x16_bf16 v[0:15], v[148:151], v[236:239], v[0:15]
	ds_read_b64_tr_b16 v[236:237], v180 offset:5632
	ds_read_b64_tr_b16 v[238:239], v180 offset:7680
	s_cmp_eq_u64 vcc, exec
	s_cselect_b64 s[40:41], -1, 0
	s_cbranch_scc1 .Lattn_fast1
	v_max_f32_e32 v194, v210, v194
	v_sub_f32_e32 v195, v210, v194
	v_mul_f32_e32 v195, 0x3dd53b94, v195
	v_exp_f32_e32 v214, v195
	v_mov_b32_e32 v210, v194
	s_branch .Lattn_join1

; #define SBAR() __builtin_amdgcn_sched_barrier(0)
; __device__ __forceinline__ void finishSM(f32x16& p0, f32x16& p1, float alpha, float& l_reg, bf16x8& pa0, bf16x8& pa1, bf16x8& pa2, bf16x8& pa3) {
; #pragma unroll
;   for (int r = 0; r < 16; ++r) p1[r] = __builtin_amdgcn_exp2f(p1[r]);
;   float ps = 0;
; #pragma unroll
;   for (int r = 0; r < 16; ++r) ps += p0[r];
; #pragma unroll
;   for (int r = 0; r < 16; ++r) ps += p1[r];
;   { auto rr = __builtin_amdgcn_permlane32_swap(__float_as_uint(ps), __float_as_uint(ps), false, false);
;     ps = __uint_as_float(rr[0]) + __uint_as_float(rr[1]); }
;   l_reg = l_reg * alpha + ps;
;     ...
;   PK4(p0, 0, pa0); PK4(p0, 8, pa1); PK4(p1, 0, pa2); PK4(p1, 8, pa3);
;     ...
; }
; __device__ __forceinline__ void qkt(f32x16& p0, f32x16& p1, const char* Ks, const bf16x8* qr, const char* qrl, int r32, int hi) {
;   p0 = f32x16{}; p1 = f32x16{};
; #pragma unroll
;   for (int d0 = 0; d0 < 8; ++d0) { int cb = (d0 * 16 + hi * 8) * 2;
;     bf16x8 b0 = *reinterpret_cast<const bf16x8*>(Ks + KSWZ(r32, cb));
;     bf16x8 b1 = *reinterpret_cast<const bf16x8*>(Ks + KSWZ(32 + r32, cb));
;     p0 = __builtin_amdgcn_mfma_f32_32x32x16_bf16(b0, qr[d0], p0, 0, 0, 0);
;     p1 = __builtin_amdgcn_mfma_f32_32x32x16_bf16(b1, qr[d0], p1, 0, 0, 0); }
; #pragma unroll
;   for (int d0 = 8; d0 < 12; ++d0) { int cb = (d0 * 16 + hi * 8) * 2;
;     bf16x8 b0 = *reinterpret_cast<const bf16x8*>(Ks + KSWZ(r32, cb));
;     bf16x8 b1 = *reinterpret_cast<const bf16x8*>(Ks + KSWZ(32 + r32, cb));
;     bf16x8 qf = *reinterpret_cast<const bf16x8*>(qrl + (((2 * (d0 - 8) + hi) ^ ((r32 >> 1) & 7)) << 4));
;     p0 = __builtin_amdgcn_mfma_f32_32x32x16_bf16(b0, qf, p0, 0, 0, 0);
;     p1 = __builtin_amdgcn_mfma_f32_32x32x16_bf16(b1, qf, p1, 0, 0, 0); }
; }
; __device__ __forceinline__ void attn_unit(const bf16_t* __restrict__ Qb, const bf16_t* __restrict__ Kn, const bf16_t* __restrict__ Vh, const bf16_t* __restrict__ Kr,
;                                           bf16_t* GO, int seq, char* lds, const int tid) {
;     ...
;     SWRITE(bp, 0); if (j + 3 < NT) SLOAD(0, (j + 3) * KVBLK); SBAR();
.Lattn_skip_rs1:
	s_waitcnt lgkmcnt(0)
	s_barrier
	ds_read_b128 v[64:67], v199 offset:12288
	ds_read_b128 v[68:71], v199 offset:24576
	ds_read_b128 v[232:235], v205 offset:12288
	ds_read_b128 v[236:239], v205 offset:24576
	ds_read_b128 v[240:243], v206 offset:12288
	ds_read_b128 v[248:251], v206 offset:24576
	v_exp_f32_e32 v162, v162
	v_add_f32_e32 v211, v225, v228
	v_exp_f32_e32 v163, v163
	v_add_f32_e32 v211, v226, v211
	v_exp_f32_e32 v160, v160
	s_waitcnt lgkmcnt(4)
	v_mfma_f32_32x32x16_bf16 v[80:95], v[64:67], v[124:127], 0
	v_add_f32_e32 v211, v229, v211
	v_exp_f32_e32 v161, v161
	v_add_f32_e32 v211, v227, v211
	v_mfma_f32_32x32x16_bf16 v[64:79], v[68:71], v[124:127], 0
	v_exp_f32_e32 v158, v158
	v_add_f32_e32 v211, v230, v211
	v_exp_f32_e32 v159, v159
	s_waitcnt lgkmcnt(2)
	v_mfma_f32_32x32x16_bf16 v[80:95], v[232:235], v[120:123], v[80:95]
	ds_read_b128 v[232:235], v208 offset:12288
	v_add_f32_e32 v211, v223, v211
	v_exp_f32_e32 v156, v156
	v_add_f32_e32 v211, v224, v211
	v_mfma_f32_32x32x16_bf16 v[64:79], v[236:239], v[120:123], v[64:79]
	ds_read_b128 v[236:239], v208 offset:24576
	v_exp_f32_e32 v157, v157
	v_add_f32_e32 v211, v219, v211
	v_exp_f32_e32 v154, v154
	s_waitcnt lgkmcnt(2)
	v_mfma_f32_32x32x16_bf16 v[80:95], v[240:243], v[116:119], v[80:95]
	ds_read_b128 v[240:243], v207 offset:12288
	v_add_f32_e32 v211, v221, v211
	v_exp_f32_e32 v155, v155
	v_add_f32_e32 v211, v220, v211
	v_mfma_f32_32x32x16_bf16 v[64:79], v[248:251], v[116:119], v[64:79]
	ds_read_b128 v[248:251], v207 offset:24576
	v_exp_f32_e32 v152, v152
	v_add_f32_e32 v211, v222, v211
	v_exp_f32_e32 v153, v153
	s_waitcnt lgkmcnt(2)
	v_mfma_f32_32x32x16_bf16 v[80:95], v[232:235], v[112:115], v[80:95]
	ds_read_b128 v[232:235], v204 offset:12288
	v_add_f32_e32 v211, v215, v211
	v_exp_f32_e32 v150, v150
	v_add_f32_e32 v211, v217, v211
	v_mfma_f32_32x32x16_bf16 v[64:79], v[236:239], v[112:115], v[64:79]
	ds_read_b128 v[236:239], v204 offset:24576
	v_exp_f32_e32 v151, v151
	v_add_f32_e32 v211, v216, v211
	v_exp_f32_e32 v148, v148
	s_waitcnt lgkmcnt(2)
	v_mfma_f32_32x32x16_bf16 v[80:95], v[240:243], v[108:111], v[80:95]
	ds_read_b128 v[240:243], v203 offset:12288
	v_add_f32_e32 v211, v218, v211
	v_exp_f32_e32 v149, v149
	v_add_f32_e32 v212, v162, v163
	v_add_f32_e32 v212, v160, v212
	v_mfma_f32_32x32x16_bf16 v[64:79], v[248:251], v[108:111], v[64:79]
	ds_read_b128 v[248:251], v203 offset:24576
	v_add_f32_e32 v212, v161, v212
	v_add_f32_e32 v212, v158, v212
	v_add_f32_e32 v212, v159, v212
	v_add_f32_e32 v212, v156, v212
	v_add_f32_e32 v212, v157, v212
	s_waitcnt lgkmcnt(2)
	v_mfma_f32_32x32x16_bf16 v[80:95], v[232:235], v[104:107], v[80:95]
	ds_read_b128 v[232:235], v200 offset:12288
	v_add_f32_e32 v212, v154, v212
	v_add_f32_e32 v212, v155, v212
	v_add_f32_e32 v212, v152, v212
	v_add_f32_e32 v212, v153, v212
	v_add_f32_e32 v212, v150, v212
	v_mfma_f32_32x32x16_bf16 v[64:79], v[236:239], v[104:107], v[64:79]
	ds_read_b128 v[236:239], v200 offset:24576
	v_add_f32_e32 v212, v151, v212
	v_add_f32_e32 v212, v148, v212
	v_add_f32_e32 v212, v149, v212
	v_add_f32_e32 v211, v211, v212
	v_mov_b32_e32 v212, v211
	v_add_u32_e32 v194, s31, v183
	s_waitcnt lgkmcnt(2)
	v_mfma_f32_32x32x16_bf16 v[80:95], v[240:243], v[100:103], v[80:95]
	ds_read_b128 v[240:243], v191 offset:12288
	s_waitcnt vmcnt(4)
	ds_write_b128 v194, v[140:143]
	v_add_u32_e32 v194, s31, v184
	s_add_i32 s73, s73, 2
	s_cmp_ge_u32 s73, s45
	s_waitcnt vmcnt(2)
	ds_write_b128 v194, v[144:147]
	s_cselect_b64 s[28:29], -1, 0
	ds_write_b128 v185, v[136:139] offset:36864
	v_mfma_f32_32x32x16_bf16 v[64:79], v[248:251], v[100:103], v[64:79]
	ds_read_b128 v[248:251], v202 offset:24576
	s_waitcnt vmcnt(1)
	ds_write_b128 v185, v[132:135] offset:49152
	s_and_b64 vcc, exec, s[28:29]
	s_waitcnt vmcnt(0)
	ds_write_b128 v186, v[128:131] offset:36864
	s_waitcnt lgkmcnt(7)
	v_mfma_f32_32x32x16_bf16 v[80:95], v[232:235], v[96:99], v[80:95]
	ds_read_b128 v[232:235], v182
	v_mfma_f32_32x32x16_bf16 v[64:79], v[236:239], v[96:99], v[64:79]
	ds_read_b128 v[236:239], v198 offset:12288
	s_waitcnt lgkmcnt(1)
	v_mfma_f32_32x32x16_bf16 v[80:95], v[240:243], v[232:235], v[80:95]
	ds_read_b128 v[240:243], v201 offset:24576
	v_mfma_f32_32x32x16_bf16 v[64:79], v[248:251], v[232:235], v[64:79]
	ds_read_b128 v[248:251], v181
	ds_read_b128 v[232:235], v187 offset:12288
	s_waitcnt lgkmcnt(1)
	v_mfma_f32_32x32x16_bf16 v[80:95], v[236:239], v[248:251], v[80:95]
	ds_read_b128 v[236:239], v189 offset:24576
	v_mfma_f32_32x32x16_bf16 v[64:79], v[240:243], v[248:251], v[64:79]
	ds_read_b128 v[240:243], v179
	ds_read_b128 v[248:251], v188 offset:12288
	s_waitcnt lgkmcnt(1)
	v_mfma_f32_32x32x16_bf16 v[80:95], v[232:235], v[240:243], v[80:95]
	ds_read_b128 v[232:235], v190 offset:24576
	v_mfma_f32_32x32x16_bf16 v[64:79], v[236:239], v[240:243], v[64:79]
	ds_read_b128 v[236:239], v177
	s_waitcnt lgkmcnt(0)
	v_mfma_f32_32x32x16_bf16 v[80:95], v[248:251], v[236:239], v[80:95]
	v_mfma_f32_32x32x16_bf16 v[64:79], v[232:235], v[236:239], v[64:79]
	v_lshl_add_u32 v231, s76, 14, v178
	ds_read_b64_tr_b16 v[240:241], v231 offset:0
	ds_read_b64_tr_b16 v[242:243], v231 offset:2048
	ds_read_b64_tr_b16 v[248:249], v231 offset:512
	ds_read_b64_tr_b16 v[250:251], v231 offset:2560
	ds_read_b64_tr_b16 v[232:233], v231 offset:1024
	ds_read_b64_tr_b16 v[234:235], v231 offset:3072
	ds_read_b64_tr_b16 v[236:237], v231 offset:1536
	ds_read_b64_tr_b16 v[238:239], v231 offset:3584
	s_cbranch_vccnz .LBB0_1157
	v_add_co_u32_e32 v128, vcc, 0xfffe0000, v168
	s_nop 1
	v_addc_co_u32_e32 v129, vcc, -1, v169, vcc
	global_load_dwordx4 v[140:143], v[128:129], off
	global_load_dwordx4 v[136:139], v[128:129], off offset:-256
	global_load_dwordx4 v[144:147], v[168:169], off
	global_load_dwordx4 v[132:135], v[168:169], off offset:-256
	s_nop 0
	global_load_dwordx4 v[128:131], v[166:167], off
; __device__ __forceinline__ void partialSM(f32x16& p0, f32x16& p1, float& m_reg, float& mn, float& alpha) {
;   constexpr float C = SCALE * 1.4426950408889634f;
;   float pmax = p0[0];
; #pragma unroll
;   for (int r = 1; r < 16; ++r) pmax = fmaxf(pmax, p0[r]);
; #pragma unroll
;   for (int r = 0; r < 16; ++r) pmax = fmaxf(pmax, p1[r]);
;   { auto rr = __builtin_amdgcn_permlane32_swap(__float_as_uint(pmax), __float_as_uint(pmax), false, false);
;     pmax = fmaxf(__uint_as_float(rr[0]), __uint_as_float(rr[1])); }
;   if (__builtin_expect(__all(pmax - m_reg <= THR / SCALE), 1)) { mn = m_reg; alpha = 1.f; }
;   else { mn = fmaxf(m_reg, pmax); alpha = __builtin_amdgcn_exp2f((m_reg - mn) * C); m_reg = mn; }
;   float mnC = -mn * C;
; #pragma unroll
;   for (int r = 0; r < 16; ++r) p0[r] = fmaf(p0[r], C, mnC);
; #pragma unroll
;   for (int r = 0; r < 16; ++r) p1[r] = fmaf(p1[r], C, mnC);
; #pragma unroll
;   for (int r = 0; r < 16; ++r) p0[r] = __builtin_amdgcn_exp2f(p0[r]);
; }
; __device__ __forceinline__ void finishSM(f32x16& p0, f32x16& p1, float alpha, float& l_reg, bf16x8& pa0, bf16x8& pa1, bf16x8& pa2, bf16x8& pa3) {
; #pragma unroll
;   for (int r = 0; r < 16; ++r) p1[r] = __builtin_amdgcn_exp2f(p1[r]);
;   float ps = 0;
; #pragma unroll
;   for (int r = 0; r < 16; ++r) ps += p0[r];
; #pragma unroll
;   for (int r = 0; r < 16; ++r) ps += p1[r];
;   { auto rr = __builtin_amdgcn_permlane32_swap(__float_as_uint(ps), __float_as_uint(ps), false, false);
;     ps = __uint_as_float(rr[0]) + __uint_as_float(rr[1]); }
;   l_reg = l_reg * alpha + ps;
;     ...
;   PK4(p0, 0, pa0); PK4(p0, 8, pa1); PK4(p1, 0, pa2); PK4(p1, 8, pa3);
;     ...
; }
.LBB0_1157:
	v_cvt_pk_bf16_f32 v158, v158, v159
	v_cvt_pk_bf16_f32 v159, v156, v157
	v_permlane32_swap_b32_e32 v211, v212
	v_cvt_pk_bf16_f32 v156, v162, v163
	v_cvt_pk_bf16_f32 v157, v160, v161
	v_cvt_pk_bf16_f32 v160, v154, v155
	v_cvt_pk_bf16_f32 v161, v152, v153
	v_cvt_pk_bf16_f32 v162, v150, v151
	v_cvt_pk_bf16_f32 v163, v148, v149
	v_add_f32_e32 v211, v211, v212
	v_cvt_pk_bf16_f32 v148, v225, v228
	v_cvt_pk_bf16_f32 v149, v226, v229
	v_cvt_pk_bf16_f32 v150, v227, v230
	v_cvt_pk_bf16_f32 v151, v223, v224
	v_cvt_pk_bf16_f32 v152, v219, v221
	v_cvt_pk_bf16_f32 v153, v220, v222
	v_cvt_pk_bf16_f32 v154, v215, v217
	v_cvt_pk_bf16_f32 v155, v216, v218
	v_fma_f32 v176, v214, v176, v211
	s_nop 3
	v_max3_f32 v194, v80, v81, v82
	v_max3_f32 v195, v64, v65, v66
	v_max3_f32 v194, v194, v83, v84
	v_max3_f32 v195, v195, v67, v68
	v_max3_f32 v194, v194, v85, v86
	v_max3_f32 v195, v195, v69, v70
	s_waitcnt lgkmcnt(4)
	v_mfma_f32_32x32x16_bf16 v[32:47], v[148:151], v[240:243], v[32:47]
	ds_read_b64_tr_b16 v[240:241], v231 offset:4096
	ds_read_b64_tr_b16 v[242:243], v231 offset:6144
	v_max3_f32 v194, v194, v87, v88
	v_max3_f32 v195, v195, v71, v72
	v_max3_f32 v194, v194, v89, v90
	v_max3_f32 v195, v195, v73, v74
	v_max3_f32 v194, v194, v91, v92
	v_max3_f32 v195, v195, v75, v76
	v_mfma_f32_32x32x16_bf16 v[48:63], v[148:151], v[248:251], v[48:63]
	ds_read_b64_tr_b16 v[248:249], v231 offset:4608
	ds_read_b64_tr_b16 v[250:251], v231 offset:6656
	v_max3_f32 v194, v194, v93, v94
	v_max3_f32 v195, v195, v77, v78
	v_max3_f32 v194, v194, v95, v195
	v_max_f32_e32 v194, v194, v79
	v_mov_b32_e32 v195, v194
	s_nop 1
	s_waitcnt lgkmcnt(4)
	v_mfma_f32_32x32x16_bf16 v[16:31], v[148:151], v[232:235], v[16:31]
	ds_read_b64_tr_b16 v[232:233], v231 offset:5120
	ds_read_b64_tr_b16 v[234:235], v231 offset:7168
	v_permlane32_swap_b32_e32 v194, v195
	v_max_f32_e32 v194, v194, v195
	v_sub_f32_e32 v195, v194, v210
	v_cmp_ge_f32_e32 vcc, s15, v195
	v_mfma_f32_32x32x16_bf16 v[0:15], v[148:151], v[236:239], v[0:15]
	ds_read_b64_tr_b16 v[236:237], v231 offset:5632
	ds_read_b64_tr_b16 v[238:239], v231 offset:7680
	s_cmp_eq_u64 vcc, exec
	s_cselect_b64 s[40:41], -1, 0
	s_cbranch_scc1 .Lattn_fast2
	v_max_f32_e32 v194, v210, v194
	v_sub_f32_e32 v195, v210, v194
	v_mul_f32_e32 v195, 0x3dd53b94, v195
	v_exp_f32_e32 v213, v195
	v_mov_b32_e32 v210, v194
	s_branch .Lattn_join2
